# v11: scan consumer packs the rank-2 update operand under the q==0 exec mask (drops 4 v_cndmask per block)
# speedup vs baseline: 1.0074x; 1.0005x over previous
; __device__ void phase_scan(const Params& p, char* lds) {
;     ...
;       for (int c = 0; c < NCH; ++c) {
;         const char* buf = lds + (c & 1) * SC_BUF;
;         char* yb = lds + SC_YB + (c & 1) * 8192 + (cw * 16 + c16) * 16;
;         ScBlk cur; sc_ldb(cur, buf, 0, arOff, bkOff, vOff);
.LBB0_579:
	s_waitcnt lgkmcnt(10)
	v_cndmask_b32_e64 v0, 0, 1, s[22:23]
	s_mov_b32 s24, 0x8400
	v_mul_lo_u32 v86, v0, s24
	s_and_b32 s24, s30, 1
	s_mul_i32 s24, s24, 0x8400
	s_add_i32 s31, s24, 0
	v_add_u32_e32 v223, s31, v205
	v_add_u32_e32 v231, s31, v206
	v_add_u32_e32 v232, s31, v207
	s_waitcnt lgkmcnt(1)
	v_and_b32_e32 v253, 3, v178
	v_lshlrev_b32_e32 v253, 4, v253
	v_add_u32_e32 v34, s31, v253
	v_mov_b32_e32 v38, 0
	v_mov_b32_e32 v39, 0
	v_mov_b32_e32 v40, 0
	v_mov_b32_e32 v41, 0
	v_mov_b32_e32 v122, 0
	v_mov_b32_e32 v123, 0
	v_mov_b32_e32 v124, 0
	v_mov_b32_e32 v125, 0
	v_lshl_add_u32 v175, v0, 13, v207
	ds_read_b128 v[66:69], v223 offset:8192
	ds_read_b128 v[58:61], v223 offset:8256
	ds_read_b128 v[62:65], v223 offset:12288
	ds_read_b128 v[54:57], v223 offset:12352
	ds_read_b128 v[12:15], v231 offset:16384
	ds_read_b128 v[8:11], v231 offset:16640
	ds_read_b128 v[4:7], v231 offset:16896
	ds_read_b128 v[0:3], v231 offset:17152
	ds_read_b128 v[18:21], v232 offset:25600
	ds_read_b128 v[50:53], v34 offset:24576
	ds_read_b128 v[46:49], v34 offset:24640
	v_add_u32_e32 v16, 0x6080, v86
	v_add_u32_e32 v222, v215, v86
	v_add_u32_e32 v233, v216, v86
	v_add_u32_e32 v234, v217, v86
	s_mov_b32 s34, 2
	s_mov_b32 s35, 0
	s_branch .LBB0_581

; __device__ __forceinline__ unsigned cvtpk(float lo, float hi) { f32x2 v = {lo, hi}; bf16x2_t b = __builtin_convertvector(v, bf16x2_t); return *(unsigned*)&b; }
; #define MFMA16(a, b, c) __builtin_amdgcn_mfma_f32_16x16x32_bf16((a), (b), (c), 0, 0, 0)
; __device__ void phase_scan(const Params& p, char* lds) {
;     ...
;           u32x4 b1 = {cvtpk(St0[0], St0[1]), cvtpk(St0[2], St0[3]), cvtpk(St1[0], St1[1]), cvtpk(St1[2], St1[3])};
;           u32x4 b2 = {cvtpk(St2[0], St2[1]), cvtpk(St2[2], St2[3]), cvtpk(St3[0], St3[1]), cvtpk(St3[2], St3[3])};
;           f32x4 sr = {0.f, 0.f, 0.f, 0.f}, yr = sr;
;           sr = MFMA16(*(bf16x8*)&cur.aa0, *(bf16x8*)&b1, sr); yr = MFMA16(*(bf16x8*)&cur.ar0, *(bf16x8*)&b1, yr);
;           sr = MFMA16(*(bf16x8*)&cur.aa1, *(bf16x8*)&b2, sr); yr = MFMA16(*(bf16x8*)&cur.ar1, *(bf16x8*)&b2, yr);
;           const float v1 = cur.v[0], v2 = cur.v[1], v3 = cur.v[2], v4 = cur.v[3];
;           const f32x4 s0 = cur.s[0], s1 = cur.s[1], s2 = cur.s[2], s3 = cur.s[3], s4 = cur.s[4], s5 = cur.s[5], s6 = cur.s[6], s7 = cur.s[7];
;           const float sa1 = sr[0];
;           const float sa2 = sr[1] + s0[0] * sa1 + s1[2] * v1;
;           const float sa3 = sr[2] + s0[1] * sa1 + s1[3] * v1 + s0[2] * sa2 + s2[0] * v2;
;           const float sa4 = sr[3] + s0[3] * sa1 + s2[1] * v1 + s1[0] * sa2 + s2[2] * v2 + s1[1] * sa3 + s2[3] * v3;
;           f32x4 y;
;           y[0] = yr[0] + s3[0] * sa1 + s5[2] * v1;
;           y[1] = yr[1] + s3[1] * sa1 + s5[3] * v1 + s3[2] * sa2 + s6[0] * v2;
;           y[2] = yr[2] + s3[3] * sa1 + s6[1] * v1 + s4[0] * sa2 + s6[2] * v2 + s4[1] * sa3 + s6[3] * v3;
;           y[3] = yr[3] + s4[2] * sa1 + s7[0] * v1 + s4[3] * sa2 + s7[1] * v2 + s5[0] * sa3 + s7[2] * v3 + s5[1] * sa4 + s7[3] * v4;
;           u32x4 bu = {cvtpk(sa1, v1), cvtpk(sa2, v2), cvtpk(sa3, v3), cvtpk(sa4, v4)};
;           if (q != 0) { bu[0] = 0u; bu[1] = 0u; bu[2] = 0u; bu[3] = 0u; }
;           St0 = MFMA16(*(bf16x8*)&cur.k0, *(bf16x8*)&bu, St0);
;           St1 = MFMA16(*(bf16x8*)&cur.k1, *(bf16x8*)&bu, St1);
;           St2 = MFMA16(*(bf16x8*)&cur.k2, *(bf16x8*)&bu, St2);
;           St3 = MFMA16(*(bf16x8*)&cur.k3, *(bf16x8*)&bu, St3);
.LBB0_581:
	v_cvt_pk_bf16_f32 v110, v70, v71
	v_cvt_pk_bf16_f32 v111, v72, v73
	v_cvt_pk_bf16_f32 v112, v74, v75
	v_cvt_pk_bf16_f32 v113, v76, v77
	v_cvt_pk_bf16_f32 v224, v78, v79
	v_cvt_pk_bf16_f32 v225, v80, v81
	s_waitcnt lgkmcnt(10)
	v_mfma_f32_16x16x32_bf16 v[66:69], v[66:69], v[110:113], 0
	v_cvt_pk_bf16_f32 v226, v82, v83
	v_cvt_pk_bf16_f32 v227, v84, v85
	v_add_u32_e32 v86, 0, v234
	s_waitcnt lgkmcnt(8)
	v_mfma_f32_16x16x32_bf16 v[62:65], v[62:65], v[110:113], 0
	v_add_u32_e32 v235, 0, v175
	ds_read_b128 v[236:239], v86
	ds_read_b128 v[240:243], v86 offset:64
	ds_read_b128 v[244:247], v86 offset:4096
	ds_read_b128 v[248:251], v86 offset:4160
	v_add_u32_e32 v86, 0, v233
	v_mfma_f32_16x16x32_bf16 v[58:61], v[58:61], v[224:227], v[66:69]
	v_add_u32_e32 v94, 0, v222
	v_add_u32_e32 v118, v253, v16
	ds_read_b128 v[102:105], v86
	ds_read_b128 v[98:101], v86 offset:256
	ds_read_b128 v[90:93], v86 offset:512
	ds_read_b128 v[86:89], v86 offset:768
	s_waitcnt lgkmcnt(15)
	v_mfma_f32_16x16x32_bf16 v[54:57], v[54:57], v[224:227], v[62:65]
	ds_read_b128 v[94:97], v94
	ds_read_b128 v[134:137], v118
	ds_read_b128 v[130:133], v118 offset:64
	s_waitcnt lgkmcnt(12)
	v_fmac_f32_dpp v59, v50, v58 quad_perm:[0,0,0,0] row_mask:0xf bank_mask:0xf
	v_fmac_f32_dpp v59, v52, v18 quad_perm:[1,1,1,1] row_mask:0xf bank_mask:0xf
	v_fmac_f32_dpp v60, v51, v58 quad_perm:[0,0,0,0] row_mask:0xf bank_mask:0xf
	v_fmac_f32_dpp v60, v53, v18 quad_perm:[1,1,1,1] row_mask:0xf bank_mask:0xf
	v_fmac_f32_dpp v61, v53, v58 quad_perm:[0,0,0,0] row_mask:0xf bank_mask:0xf
	v_fmac_f32_dpp v61, v51, v18 quad_perm:[2,2,2,2] row_mask:0xf bank_mask:0xf
	v_fmac_f32_dpp v60, v52, v59 quad_perm:[0,0,0,0] row_mask:0xf bank_mask:0xf
	v_fmac_f32_dpp v60, v50, v19 quad_perm:[2,2,2,2] row_mask:0xf bank_mask:0xf
	v_fmac_f32_dpp v61, v50, v59 quad_perm:[1,1,1,1] row_mask:0xf bank_mask:0xf
	v_fmac_f32_dpp v61, v52, v19 quad_perm:[2,2,2,2] row_mask:0xf bank_mask:0xf
	v_fmac_f32_dpp v61, v51, v60 quad_perm:[1,1,1,1] row_mask:0xf bank_mask:0xf
	v_fmac_f32_dpp v61, v53, v20 quad_perm:[2,2,2,2] row_mask:0xf bank_mask:0xf
	s_mov_b64 exec, s[20:21]
	v_cvt_pk_bf16_f32 v38, v58, v18
	v_cvt_pk_bf16_f32 v39, v59, v19
	v_cvt_pk_bf16_f32 v40, v60, v20
	v_cvt_pk_bf16_f32 v41, v61, v21
	s_mov_b64 exec, -1
	v_fmac_f32_dpp v54, v50, v58 quad_perm:[3,3,3,3] row_mask:0xf bank_mask:0xf
	s_waitcnt lgkmcnt(11)
	v_fmac_f32_dpp v54, v48, v18 quad_perm:[1,1,1,1] row_mask:0xf bank_mask:0xf
	v_mfma_f32_16x16x32_bf16 v[70:73], v[12:15], v[38:41], v[70:73]
	v_fmac_f32_dpp v55, v51, v58 quad_perm:[3,3,3,3] row_mask:0xf bank_mask:0xf
	v_fmac_f32_dpp v55, v49, v18 quad_perm:[1,1,1,1] row_mask:0xf bank_mask:0xf
	v_fmac_f32_dpp v55, v52, v59 quad_perm:[3,3,3,3] row_mask:0xf bank_mask:0xf
	v_fmac_f32_dpp v55, v46, v19 quad_perm:[2,2,2,2] row_mask:0xf bank_mask:0xf
	v_mfma_f32_16x16x32_bf16 v[74:77], v[8:11], v[38:41], v[74:77]
	v_fmac_f32_dpp v56, v53, v58 quad_perm:[3,3,3,3] row_mask:0xf bank_mask:0xf
	v_fmac_f32_dpp v56, v47, v18 quad_perm:[2,2,2,2] row_mask:0xf bank_mask:0xf
	v_fmac_f32_dpp v56, v46, v59 quad_perm:[0,0,0,0] row_mask:0xf bank_mask:0xf
	v_fmac_f32_dpp v56, v48, v19 quad_perm:[2,2,2,2] row_mask:0xf bank_mask:0xf
	v_fmac_f32_dpp v56, v47, v60 quad_perm:[0,0,0,0] row_mask:0xf bank_mask:0xf
	v_fmac_f32_dpp v56, v49, v20 quad_perm:[2,2,2,2] row_mask:0xf bank_mask:0xf
	v_mfma_f32_16x16x32_bf16 v[78:81], v[4:7], v[38:41], v[78:81]
	v_fmac_f32_dpp v57, v48, v58 quad_perm:[0,0,0,0] row_mask:0xf bank_mask:0xf
	v_fmac_f32_dpp v57, v46, v18 quad_perm:[3,3,3,3] row_mask:0xf bank_mask:0xf
	v_fmac_f32_dpp v57, v49, v59 quad_perm:[0,0,0,0] row_mask:0xf bank_mask:0xf
	v_fmac_f32_dpp v57, v47, v19 quad_perm:[3,3,3,3] row_mask:0xf bank_mask:0xf
	v_mfma_f32_16x16x32_bf16 v[82:85], v[0:3], v[38:41], v[82:85]
	v_fmac_f32_dpp v57, v46, v60 quad_perm:[1,1,1,1] row_mask:0xf bank_mask:0xf
	v_fmac_f32_dpp v57, v48, v20 quad_perm:[3,3,3,3] row_mask:0xf bank_mask:0xf
	v_fmac_f32_dpp v57, v47, v61 quad_perm:[1,1,1,1] row_mask:0xf bank_mask:0xf
	v_fmac_f32_dpp v57, v49, v21 quad_perm:[3,3,3,3] row_mask:0xf bank_mask:0xf
	v_add_u32_e32 v0, 0x16800, v235
	ds_write_b128 v0, v[54:57]
	v_cvt_pk_bf16_f32 v26, v70, v71
	v_cvt_pk_bf16_f32 v27, v72, v73
	v_cvt_pk_bf16_f32 v28, v74, v75
	v_cvt_pk_bf16_f32 v29, v76, v77
	v_cvt_pk_bf16_f32 v224, v78, v79
	v_cvt_pk_bf16_f32 v225, v80, v81
	s_waitcnt lgkmcnt(11)
	v_mfma_f32_16x16x32_bf16 v[30:33], v[236:239], v[26:29], 0
	v_cvt_pk_bf16_f32 v226, v82, v83
	v_cvt_pk_bf16_f32 v227, v84, v85
	s_and_b32 s24, s34, 6
	s_waitcnt lgkmcnt(9)
; #define MFMA16(a, b, c) __builtin_amdgcn_mfma_f32_16x16x32_bf16((a), (b), (c), 0, 0, 0)
; __device__ void phase_scan(const Params& p, char* lds) {
;     ...
;           u32x4 b1 = {cvtpk(St0[0], St0[1]), cvtpk(St0[2], St0[3]), cvtpk(St1[0], St1[1]), cvtpk(St1[2], St1[3])};
;           u32x4 b2 = {cvtpk(St2[0], St2[1]), cvtpk(St2[2], St2[3]), cvtpk(St3[0], St3[1]), cvtpk(St3[2], St3[3])};
;           f32x4 sr = {0.f, 0.f, 0.f, 0.f}, yr = sr;
;           sr = MFMA16(*(bf16x8*)&cur.aa0, *(bf16x8*)&b1, sr); yr = MFMA16(*(bf16x8*)&cur.ar0, *(bf16x8*)&b1, yr);
;           sr = MFMA16(*(bf16x8*)&cur.aa1, *(bf16x8*)&b2, sr); yr = MFMA16(*(bf16x8*)&cur.ar1, *(bf16x8*)&b2, yr);
;           const float v1 = cur.v[0], v2 = cur.v[1], v3 = cur.v[2], v4 = cur.v[3];
;           const f32x4 s0 = cur.s[0], s1 = cur.s[1], s2 = cur.s[2], s3 = cur.s[3], s4 = cur.s[4], s5 = cur.s[5], s6 = cur.s[6], s7 = cur.s[7];
;           const float sa1 = sr[0];
;           const float sa2 = sr[1] + s0[0] * sa1 + s1[2] * v1;
;           const float sa3 = sr[2] + s0[1] * sa1 + s1[3] * v1 + s0[2] * sa2 + s2[0] * v2;
;           const float sa4 = sr[3] + s0[3] * sa1 + s2[1] * v1 + s1[0] * sa2 + s2[2] * v2 + s1[1] * sa3 + s2[3] * v3;
;           f32x4 y;
;           y[0] = yr[0] + s3[0] * sa1 + s5[2] * v1;
;           y[1] = yr[1] + s3[1] * sa1 + s5[3] * v1 + s3[2] * sa2 + s6[0] * v2;
;           y[2] = yr[2] + s3[3] * sa1 + s6[1] * v1 + s4[0] * sa2 + s6[2] * v2 + s4[1] * sa3 + s6[3] * v3;
;           y[3] = yr[3] + s4[2] * sa1 + s7[0] * v1 + s4[3] * sa2 + s7[1] * v2 + s5[0] * sa3 + s7[2] * v3 + s5[1] * sa4 + s7[3] * v4;
;           u32x4 bu = {cvtpk(sa1, v1), cvtpk(sa2, v2), cvtpk(sa3, v3), cvtpk(sa4, v4)};
;           if (q != 0) { bu[0] = 0u; bu[1] = 0u; bu[2] = 0u; bu[3] = 0u; }
;           St0 = MFMA16(*(bf16x8*)&cur.k0, *(bf16x8*)&bu, St0);
;           St1 = MFMA16(*(bf16x8*)&cur.k1, *(bf16x8*)&bu, St1);
;           St2 = MFMA16(*(bf16x8*)&cur.k2, *(bf16x8*)&bu, St2);
;           St3 = MFMA16(*(bf16x8*)&cur.k3, *(bf16x8*)&bu, St3);
;           *(f32x4*)(yb + blk * 1024) = y;
;           cur = nxt;
;           if (blk == 7) {
;             const char* pw = buf + SC_P + 31 * 256 + wOff;
;             St0 *= *(const f32x4*)(pw); St1 *= *(const f32x4*)(pw + 64); St2 *= *(const f32x4*)(pw + 128); St3 *= *(const f32x4*)(pw + 192);
;           }
;           if (blk == 3 || blk == 7) __syncthreads();
	v_mfma_f32_16x16x32_bf16 v[236:239], v[244:247], v[26:29], 0
	v_lshl_add_u32 v0, s24, 9, v223
	s_lshl_b32 s25, s24, 10
	s_lshl_b32 s24, s24, 7
	v_mfma_f32_16x16x32_bf16 v[240:243], v[240:243], v[224:227], v[30:33]
	ds_read_b128 v[66:69], v0 offset:8192
	ds_read_b128 v[58:61], v0 offset:8256
	ds_read_b128 v[62:65], v0 offset:12288
	ds_read_b128 v[54:57], v0 offset:12352
	v_add_u32_e32 v0, s25, v231
	v_add_u32_e32 v18, s25, v232
	s_waitcnt lgkmcnt(12)
	v_mfma_f32_16x16x32_bf16 v[224:227], v[248:251], v[224:227], v[236:239]
	s_add_i32 s24, s31, s24
	ds_read_b128 v[12:15], v0 offset:16384
	ds_read_b128 v[8:11], v0 offset:16640
	ds_read_b128 v[4:7], v0 offset:16896
	ds_read_b128 v[0:3], v0 offset:17152
	s_waitcnt lgkmcnt(10)
	v_fmac_f32_dpp v241, v134, v240 quad_perm:[0,0,0,0] row_mask:0xf bank_mask:0xf
	v_fmac_f32_dpp v241, v136, v94 quad_perm:[1,1,1,1] row_mask:0xf bank_mask:0xf
	v_fmac_f32_dpp v242, v135, v240 quad_perm:[0,0,0,0] row_mask:0xf bank_mask:0xf
	v_fmac_f32_dpp v242, v137, v94 quad_perm:[1,1,1,1] row_mask:0xf bank_mask:0xf
	v_fmac_f32_dpp v243, v137, v240 quad_perm:[0,0,0,0] row_mask:0xf bank_mask:0xf
	v_fmac_f32_dpp v243, v135, v94 quad_perm:[2,2,2,2] row_mask:0xf bank_mask:0xf
	v_fmac_f32_dpp v242, v136, v241 quad_perm:[0,0,0,0] row_mask:0xf bank_mask:0xf
	v_fmac_f32_dpp v242, v134, v95 quad_perm:[2,2,2,2] row_mask:0xf bank_mask:0xf
	v_fmac_f32_dpp v243, v134, v241 quad_perm:[1,1,1,1] row_mask:0xf bank_mask:0xf
	v_fmac_f32_dpp v243, v136, v95 quad_perm:[2,2,2,2] row_mask:0xf bank_mask:0xf
	v_fmac_f32_dpp v243, v135, v242 quad_perm:[1,1,1,1] row_mask:0xf bank_mask:0xf
	v_fmac_f32_dpp v243, v137, v96 quad_perm:[2,2,2,2] row_mask:0xf bank_mask:0xf
	s_mov_b64 exec, s[20:21]
	v_cvt_pk_bf16_f32 v122, v240, v94
	v_cvt_pk_bf16_f32 v123, v241, v95
	v_cvt_pk_bf16_f32 v124, v242, v96
	v_cvt_pk_bf16_f32 v125, v243, v97
	s_mov_b64 exec, -1
	v_fmac_f32_dpp v224, v134, v240 quad_perm:[3,3,3,3] row_mask:0xf bank_mask:0xf
	s_waitcnt lgkmcnt(9)
	v_fmac_f32_dpp v224, v132, v94 quad_perm:[1,1,1,1] row_mask:0xf bank_mask:0xf
	v_mfma_f32_16x16x32_bf16 v[70:73], v[102:105], v[122:125], v[70:73]
	v_fmac_f32_dpp v225, v135, v240 quad_perm:[3,3,3,3] row_mask:0xf bank_mask:0xf
	v_fmac_f32_dpp v225, v133, v94 quad_perm:[1,1,1,1] row_mask:0xf bank_mask:0xf
	v_fmac_f32_dpp v225, v136, v241 quad_perm:[3,3,3,3] row_mask:0xf bank_mask:0xf
	v_fmac_f32_dpp v225, v130, v95 quad_perm:[2,2,2,2] row_mask:0xf bank_mask:0xf
	v_mfma_f32_16x16x32_bf16 v[74:77], v[98:101], v[122:125], v[74:77]
	v_fmac_f32_dpp v226, v137, v240 quad_perm:[3,3,3,3] row_mask:0xf bank_mask:0xf
	v_fmac_f32_dpp v226, v131, v94 quad_perm:[2,2,2,2] row_mask:0xf bank_mask:0xf
	v_fmac_f32_dpp v226, v130, v241 quad_perm:[0,0,0,0] row_mask:0xf bank_mask:0xf
	v_fmac_f32_dpp v226, v132, v95 quad_perm:[2,2,2,2] row_mask:0xf bank_mask:0xf
	v_fmac_f32_dpp v226, v131, v242 quad_perm:[0,0,0,0] row_mask:0xf bank_mask:0xf
	v_fmac_f32_dpp v226, v133, v96 quad_perm:[2,2,2,2] row_mask:0xf bank_mask:0xf
	v_mfma_f32_16x16x32_bf16 v[78:81], v[90:93], v[122:125], v[78:81]
	v_add_u32_e32 v34, s24, v253
	ds_read_b128 v[18:21], v18 offset:25600
	ds_read_b128 v[50:53], v34 offset:24576
	ds_read_b128 v[46:49], v34 offset:24640
	v_fmac_f32_dpp v227, v132, v240 quad_perm:[0,0,0,0] row_mask:0xf bank_mask:0xf
	v_fmac_f32_dpp v227, v130, v94 quad_perm:[3,3,3,3] row_mask:0xf bank_mask:0xf
	v_fmac_f32_dpp v227, v133, v241 quad_perm:[0,0,0,0] row_mask:0xf bank_mask:0xf
	v_fmac_f32_dpp v227, v131, v95 quad_perm:[3,3,3,3] row_mask:0xf bank_mask:0xf
	v_fmac_f32_dpp v227, v130, v242 quad_perm:[1,1,1,1] row_mask:0xf bank_mask:0xf
	v_fmac_f32_dpp v227, v132, v96 quad_perm:[3,3,3,3] row_mask:0xf bank_mask:0xf
	v_fmac_f32_dpp v227, v131, v243 quad_perm:[1,1,1,1] row_mask:0xf bank_mask:0xf
	v_fmac_f32_dpp v227, v133, v97 quad_perm:[3,3,3,3] row_mask:0xf bank_mask:0xf
	v_mfma_f32_16x16x32_bf16 v[82:85], v[86:89], v[122:125], v[82:85]
	s_cmp_lg_u32 s34, 8
	v_add_u32_e32 v86, 0x16c00, v235
	ds_write_b128 v86, v[224:227]
	s_cbranch_scc1 .LBB0_583
	v_add_u32_e32 v98, s31, v204
	ds_read_b128 v[86:89], v98 offset:7936
	ds_read_b128 v[90:93], v98 offset:8000
	ds_read_b128 v[94:97], v98 offset:8064
	ds_read_b128 v[98:101], v98 offset:8128
	s_waitcnt lgkmcnt(3)
	v_mul_f32_e64 v72, v72, v88
	v_mul_f32_e64 v73, v73, v89
	v_mul_f32_e64 v70, v70, v86
	v_mul_f32_e64 v71, v71, v87
	s_waitcnt lgkmcnt(2)
	v_mul_f32_e64 v76, v76, v92
	v_mul_f32_e64 v77, v77, v93
	v_mul_f32_e64 v74, v74, v90
	v_mul_f32_e64 v75, v75, v91
	s_waitcnt lgkmcnt(1)
	v_mul_f32_e64 v80, v80, v96
	v_mul_f32_e64 v81, v81, v97
	v_mul_f32_e64 v78, v78, v94
	v_mul_f32_e64 v79, v79, v95
	s_waitcnt lgkmcnt(0)
	v_mul_f32_e64 v84, v84, v100
	v_mul_f32_e64 v85, v85, v101
	v_mul_f32_e64 v82, v82, v98
	v_mul_f32_e64 v83, v83, v99
